# local barriers v2: per-WG arrival slots in one L2 line per XCC (plain store + sc1 poll by 32 lanes), no atomics
# speedup vs baseline: 1.0409x; 1.0074x over previous
.LBB0_262:
	s_cmp_gt_i32 s69, 3
	s_cselect_b64 s[0:1], -1, 0
	s_and_b64 s[2:3], s[4:5], s[0:1]
	s_andn2_b64 vcc, exec, s[2:3]
	s_cbranch_vccnz .LBB0_316
	s_waitcnt vmcnt(0)
	s_waitcnt vmcnt(0) lgkmcnt(0)
	s_barrier
	v_mov_b32_e32 v0, 0x20040
	ds_read_b32 v2, v0
	ds_read_b32 v3, v0 offset:16
	ds_read_b32 v5, v0 offset:8
	s_lshl_b32 s2, s33, 7
	s_add_u32 s2, s2, 0x3600
	v_lshl_add_u32 v0, v199, 2, s2
	v_mov_b32_e32 v6, 1
	s_waitcnt lgkmcnt(0)
	v_cmp_eq_u32_e32 vcc, 0, v3
	s_cbranch_vccnz .Lxl_orig_2
	v_cmp_lt_u32_e32 vcc, 32, v2
	s_cbranch_vccnz .Lxl_orig_2
	v_lshl_add_u32 v1, v5, 2, s2
	v_cmp_lt_u32_e32 vcc, v199, v2
	s_and_saveexec_b64 s[4:5], vcc
	s_cbranch_execz .LBB0_315
	v_cmp_eq_u32_e32 vcc, 0, v199
	s_and_saveexec_b64 s[2:3], vcc
	global_store_dword v1, v6, s[92:93]
	s_mov_b64 exec, s[2:3]
	buffer_inv sc1
	s_mov_b32 s2, 0x20000
.Lxl_poll_2:
	global_load_dword v4, v0, s[92:93] sc1
	s_waitcnt vmcnt(0)
	v_cmp_gt_u32_e32 vcc, 1, v4
	s_cbranch_vccz .LBB0_315
	s_sleep 1
	s_sub_u32 s2, s2, 1
	s_cmp_lg_u32 s2, 0
	s_cbranch_scc1 .Lxl_poll_2
	s_branch .LBB0_315
.Lxl_orig_2:
	s_mov_b64 s[4:5], exec
	v_readlane_b32 s2, v255, 1
	v_readlane_b32 s3, v255, 2
	s_and_b64 s[2:3], s[4:5], s[2:3]
	s_mov_b64 exec, s[2:3]
	s_cbranch_execz .LBB0_315
	s_add_i32 s2, 0, 0x20040
	v_mov_b32_e32 v0, s2
	s_waitcnt vmcnt(0) expcnt(0) lgkmcnt(0)
	ds_read_b32 v2, v0
	s_add_i32 s2, 0, 0x20044
	v_mov_b32_e32 v0, s2
	ds_read_b32 v0, v0
	s_waitcnt lgkmcnt(1)
	v_cmp_ne_u32_e32 vcc, 0, v2
	s_cbranch_vccnz .LBB0_279
	s_add_u32 s6, s30, 0xfc00200
	s_addc_u32 s7, s31, 0
	s_add_u32 s8, s30, 0xfc00400
	s_addc_u32 s9, s31, 0
	s_add_u32 s12, s30, 0xfc00500
	s_addc_u32 s13, s31, 0
	s_add_u32 s16, s30, 0xfc00600
	s_addc_u32 s17, s31, 0
	s_add_u32 s18, s30, 0xfc00700
	s_addc_u32 s19, s31, 0
	s_add_u32 s20, s30, 0xfc00800
	s_addc_u32 s21, s31, 0
	s_add_u32 s24, s30, 0xfc00900
	s_addc_u32 s25, s31, 0
	s_add_u32 s26, s30, 0xfc00a00
	s_addc_u32 s27, s31, 0
	s_add_u32 s50, s30, 0xfc00b00
	s_addc_u32 s51, s31, 0
	s_add_u32 s56, s30, 0xfc00c00
	s_addc_u32 s57, s31, 0
	s_add_u32 s58, s30, 0xfc00d00
	s_addc_u32 s59, s31, 0
	s_add_u32 s60, s30, 0xfc00e00
	s_addc_u32 s61, s31, 0
	s_add_u32 s62, s30, 0xfc00f00
	s_addc_u32 s63, s31, 0
	s_add_u32 s64, s30, 0xfc01000
	s_addc_u32 s65, s31, 0
	s_add_u32 s66, s30, 0xfc01100
	s_addc_u32 s67, s31, 0
	s_add_u32 s76, s30, 0xfc01200
	v_readlane_b32 s2, v255, 0
	s_addc_u32 s77, s31, 0
	s_mul_i32 s2, s35, s2
	s_add_u32 s78, s30, 0xfc01300
	s_mov_b32 s22, s80
	s_mov_b64 s[14:15], s[92:93]
	s_mul_i32 s2, s2, s34
	s_addc_u32 s79, s31, 0
	s_mov_b32 s3, 1
	v_mov_b32_e32 v16, 0
	s_branch .LBB0_267

.LBB0_363:
	s_cmp_gt_i32 s69, 4
	s_cselect_b64 s[0:1], -1, 0
	s_and_b64 s[2:3], s[8:9], s[0:1]
	s_andn2_b64 vcc, exec, s[2:3]
	s_cbranch_vccnz .LBB0_417
	s_waitcnt vmcnt(0)
	s_waitcnt vmcnt(0) lgkmcnt(0)
	s_barrier
	v_mov_b32_e32 v0, 0x20040
	ds_read_b32 v2, v0
	ds_read_b32 v3, v0 offset:16
	ds_read_b32 v5, v0 offset:8
	s_lshl_b32 s2, s33, 7
	s_add_u32 s2, s2, 0x3600
	v_lshl_add_u32 v0, v199, 2, s2
	v_mov_b32_e32 v6, 2
	s_waitcnt lgkmcnt(0)
	v_cmp_eq_u32_e32 vcc, 0, v3
	s_cbranch_vccnz .Lxl_orig_3
	v_cmp_lt_u32_e32 vcc, 32, v2
	s_cbranch_vccnz .Lxl_orig_3
	v_lshl_add_u32 v1, v5, 2, s2
	v_cmp_lt_u32_e32 vcc, v199, v2
	s_and_saveexec_b64 s[4:5], vcc
	s_cbranch_execz .LBB0_416
	v_cmp_eq_u32_e32 vcc, 0, v199
	s_and_saveexec_b64 s[2:3], vcc
	global_store_dword v1, v6, s[92:93]
	s_mov_b64 exec, s[2:3]
	buffer_inv sc1
	s_mov_b32 s2, 0x20000
.Lxl_poll_3:
	global_load_dword v4, v0, s[92:93] sc1
	s_waitcnt vmcnt(0)
	v_cmp_gt_u32_e32 vcc, 2, v4
	s_cbranch_vccz .LBB0_416
	s_sleep 1
	s_sub_u32 s2, s2, 1
	s_cmp_lg_u32 s2, 0
	s_cbranch_scc1 .Lxl_poll_3
	s_branch .LBB0_416
.Lxl_orig_3:
	s_mov_b64 s[4:5], exec
	v_readlane_b32 s2, v255, 1
	v_readlane_b32 s3, v255, 2
	s_and_b64 s[2:3], s[4:5], s[2:3]
	s_mov_b64 exec, s[2:3]
	s_cbranch_execz .LBB0_416
	s_add_i32 s2, 0, 0x20040
	v_mov_b32_e32 v0, s2
	s_waitcnt vmcnt(0) expcnt(0) lgkmcnt(0)
	ds_read_b32 v2, v0
	s_add_i32 s2, 0, 0x20044
	v_mov_b32_e32 v0, s2
	ds_read_b32 v0, v0
	s_waitcnt lgkmcnt(1)
	v_cmp_ne_u32_e32 vcc, 0, v2
	s_cbranch_vccnz .LBB0_380
	s_add_u32 s6, s30, 0xfc00200
	s_addc_u32 s7, s31, 0
	s_add_u32 s8, s30, 0xfc00400
	s_addc_u32 s9, s31, 0
	s_add_u32 s12, s30, 0xfc00500
	s_addc_u32 s13, s31, 0
	s_add_u32 s18, s30, 0xfc00600
	s_addc_u32 s19, s31, 0
	s_add_u32 s20, s30, 0xfc00700
	s_addc_u32 s21, s31, 0
	s_add_u32 s24, s30, 0xfc00800
	s_addc_u32 s25, s31, 0
	s_add_u32 s26, s30, 0xfc00900
	s_addc_u32 s27, s31, 0
	s_add_u32 s42, s30, 0xfc00a00
	s_addc_u32 s43, s31, 0
	s_add_u32 s50, s30, 0xfc00b00
	s_addc_u32 s51, s31, 0
	s_add_u32 s52, s30, 0xfc00c00
	s_addc_u32 s53, s31, 0
	s_add_u32 s54, s30, 0xfc00d00
	s_addc_u32 s55, s31, 0
	s_add_u32 s56, s30, 0xfc00e00
	s_addc_u32 s57, s31, 0
	s_add_u32 s58, s30, 0xfc00f00
	s_addc_u32 s59, s31, 0
	s_add_u32 s60, s30, 0xfc01000
	s_addc_u32 s61, s31, 0
	s_add_u32 s62, s30, 0xfc01100
	s_addc_u32 s63, s31, 0
	s_add_u32 s64, s30, 0xfc01200
	v_readlane_b32 s2, v255, 0
	s_addc_u32 s65, s31, 0
	s_mul_i32 s2, s35, s2
	s_add_u32 s66, s30, 0xfc01300
	s_mul_i32 s2, s2, s34
	s_addc_u32 s67, s31, 0
	s_mov_b32 s3, 1
	v_mov_b32_e32 v16, 0
	s_branch .LBB0_368

.LBB0_1502:
	s_cmp_gt_i32 s69, 7
	s_cselect_b64 s[2:3], -1, 0
	s_and_b64 s[0:1], s[0:1], s[2:3]
	s_andn2_b64 vcc, exec, s[0:1]
	s_cbranch_vccnz .LBB0_1556
	s_waitcnt vmcnt(0)
	s_waitcnt vmcnt(0) lgkmcnt(0)
	s_barrier
	v_mov_b32_e32 v0, 0x20040
	ds_read_b32 v2, v0
	ds_read_b32 v3, v0 offset:16
	ds_read_b32 v5, v0 offset:8
	s_lshl_b32 s4, s33, 7
	s_add_u32 s4, s4, 0x3600
	v_lshl_add_u32 v0, v199, 2, s4
	v_mov_b32_e32 v6, 3
	s_waitcnt lgkmcnt(0)
	v_cmp_eq_u32_e32 vcc, 0, v3
	s_cbranch_vccnz .Lxl_orig_6
	v_cmp_lt_u32_e32 vcc, 32, v2
	s_cbranch_vccnz .Lxl_orig_6
	v_lshl_add_u32 v1, v5, 2, s4
	v_cmp_lt_u32_e32 vcc, v199, v2
	s_and_saveexec_b64 s[0:1], vcc
	s_cbranch_execz .LBB0_1555
	v_cmp_eq_u32_e32 vcc, 0, v199
	s_and_saveexec_b64 s[4:5], vcc
	global_store_dword v1, v6, s[92:93]
	s_mov_b64 exec, s[4:5]
	buffer_inv sc1
	s_mov_b32 s4, 0x20000
.Lxl_poll_6:
	global_load_dword v4, v0, s[92:93] sc1
	s_waitcnt vmcnt(0)
	v_cmp_gt_u32_e32 vcc, 3, v4
	s_cbranch_vccz .LBB0_1555
	s_sleep 1
	s_sub_u32 s4, s4, 1
	s_cmp_lg_u32 s4, 0
	s_cbranch_scc1 .Lxl_poll_6
	s_branch .LBB0_1555
.Lxl_orig_6:
	s_mov_b64 s[0:1], exec
	v_readlane_b32 s4, v255, 1
	v_readlane_b32 s5, v255, 2
	s_and_b64 s[4:5], s[0:1], s[4:5]
	s_mov_b64 exec, s[4:5]
	s_cbranch_execz .LBB0_1555
	s_add_i32 s4, 0, 0x20040
	v_mov_b32_e32 v0, s4
	s_waitcnt vmcnt(0) expcnt(0) lgkmcnt(0)
	ds_read_b32 v2, v0
	s_add_i32 s4, 0, 0x20044
	v_mov_b32_e32 v0, s4
	ds_read_b32 v0, v0
	s_waitcnt lgkmcnt(1)
	v_cmp_ne_u32_e32 vcc, 0, v2
	s_cbranch_vccnz .LBB0_1519
	v_readlane_b32 s4, v255, 0
	s_mul_i32 s16, s35, s4
	s_add_u32 s4, s30, 0xfc00200
	s_addc_u32 s5, s31, 0
	s_add_u32 s6, s30, 0xfc00400
	s_addc_u32 s7, s31, 0
	s_add_u32 s8, s30, 0xfc00500
	s_addc_u32 s9, s31, 0
	s_add_u32 s12, s30, 0xfc00600
	s_addc_u32 s13, s31, 0
	s_add_u32 s14, s30, 0xfc00700
	s_addc_u32 s15, s31, 0
	s_add_u32 s18, s30, 0xfc00800
	s_addc_u32 s19, s31, 0
	s_add_u32 s20, s30, 0xfc00900
	s_addc_u32 s21, s31, 0
	s_add_u32 s24, s30, 0xfc00a00
	s_addc_u32 s25, s31, 0
	s_add_u32 s26, s30, 0xfc00b00
	s_addc_u32 s27, s31, 0
	s_add_u32 s42, s30, 0xfc00c00
	s_addc_u32 s43, s31, 0
	s_add_u32 s44, s30, 0xfc00d00
	s_addc_u32 s45, s31, 0
	s_add_u32 s46, s30, 0xfc00e00
	s_addc_u32 s47, s31, 0
	s_add_u32 s48, s30, 0xfc00f00
	s_addc_u32 s49, s31, 0
	s_add_u32 s50, s30, 0xfc01000
	s_addc_u32 s51, s31, 0
	s_add_u32 s52, s30, 0xfc01100
	s_addc_u32 s53, s31, 0
	s_add_u32 s54, s30, 0xfc01200
	s_addc_u32 s55, s31, 0
	s_add_u32 s56, s30, 0xfc01300
	s_mul_i32 s16, s16, s34
	s_addc_u32 s57, s31, 0
	s_mov_b32 s17, 1
	v_mov_b32_e32 v16, 0
	s_branch .LBB0_1507

.LBB0_1599:
	s_cmp_gt_i32 s69, 8
	s_cselect_b64 s[2:3], -1, 0
	s_and_b64 s[0:1], s[0:1], s[2:3]
	v_readlane_b32 s60, v255, 20
	s_andn2_b64 vcc, exec, s[0:1]
	v_readlane_b32 s61, v255, 21
	s_cbranch_vccnz .LBB0_1653
	s_waitcnt vmcnt(0)
	s_waitcnt vmcnt(0) lgkmcnt(0)
	s_barrier
	v_mov_b32_e32 v0, 0x20040
	ds_read_b32 v2, v0
	ds_read_b32 v3, v0 offset:16
	ds_read_b32 v5, v0 offset:8
	s_lshl_b32 s4, s33, 7
	s_add_u32 s4, s4, 0x3600
	v_lshl_add_u32 v0, v199, 2, s4
	v_mov_b32_e32 v6, 4
	s_waitcnt lgkmcnt(0)
	v_cmp_eq_u32_e32 vcc, 0, v3
	s_cbranch_vccnz .Lxl_orig_7
	v_cmp_lt_u32_e32 vcc, 32, v2
	s_cbranch_vccnz .Lxl_orig_7
	v_lshl_add_u32 v1, v5, 2, s4
	v_cmp_lt_u32_e32 vcc, v199, v2
	s_and_saveexec_b64 s[0:1], vcc
	s_cbranch_execz .LBB0_1652
	v_cmp_eq_u32_e32 vcc, 0, v199
	s_and_saveexec_b64 s[4:5], vcc
	global_store_dword v1, v6, s[92:93]
	s_mov_b64 exec, s[4:5]
	buffer_inv sc1
	s_mov_b32 s4, 0x20000
.Lxl_poll_7:
	global_load_dword v4, v0, s[92:93] sc1
	s_waitcnt vmcnt(0)
	v_cmp_gt_u32_e32 vcc, 4, v4
	s_cbranch_vccz .LBB0_1652
	s_sleep 1
	s_sub_u32 s4, s4, 1
	s_cmp_lg_u32 s4, 0
	s_cbranch_scc1 .Lxl_poll_7
	s_branch .LBB0_1652
.Lxl_orig_7:
	s_mov_b64 s[0:1], exec
	v_readlane_b32 s4, v255, 1
	v_readlane_b32 s5, v255, 2
	s_and_b64 s[4:5], s[0:1], s[4:5]
	s_mov_b64 exec, s[4:5]
	s_cbranch_execz .LBB0_1652
	s_add_i32 s4, 0, 0x20040
	v_mov_b32_e32 v0, s4
	s_waitcnt vmcnt(0) expcnt(0) lgkmcnt(0)
	ds_read_b32 v2, v0
	s_add_i32 s4, 0, 0x20044
	v_mov_b32_e32 v0, s4
	ds_read_b32 v0, v0
	s_waitcnt lgkmcnt(1)
	v_cmp_ne_u32_e32 vcc, 0, v2
	s_cbranch_vccnz .LBB0_1616
	v_readlane_b32 s4, v255, 0
	s_mul_i32 s16, s35, s4
	s_add_u32 s4, s30, 0xfc00200
	s_addc_u32 s5, s31, 0
	s_add_u32 s6, s30, 0xfc00400
	s_addc_u32 s7, s31, 0
	s_add_u32 s8, s30, 0xfc00500
	s_addc_u32 s9, s31, 0
	s_add_u32 s12, s30, 0xfc00600
	s_addc_u32 s13, s31, 0
	s_add_u32 s14, s30, 0xfc00700
	s_addc_u32 s15, s31, 0
	s_add_u32 s18, s30, 0xfc00800
	s_addc_u32 s19, s31, 0
	s_add_u32 s20, s30, 0xfc00900
	s_addc_u32 s21, s31, 0
	s_add_u32 s22, s30, 0xfc00a00
	s_addc_u32 s23, s31, 0
	s_add_u32 s24, s30, 0xfc00b00
	s_addc_u32 s25, s31, 0
	s_add_u32 s26, s30, 0xfc00c00
	s_addc_u32 s27, s31, 0
	s_add_u32 s42, s30, 0xfc00d00
	s_addc_u32 s43, s31, 0
	s_add_u32 s44, s30, 0xfc00e00
	s_addc_u32 s45, s31, 0
	s_add_u32 s46, s30, 0xfc00f00
	s_addc_u32 s47, s31, 0
	s_add_u32 s48, s30, 0xfc01000
	s_addc_u32 s49, s31, 0
	s_add_u32 s50, s30, 0xfc01100
	s_addc_u32 s51, s31, 0
	s_add_u32 s52, s30, 0xfc01200
	s_addc_u32 s53, s31, 0
	s_add_u32 s54, s30, 0xfc01300
	s_mul_i32 s16, s16, s34
	s_addc_u32 s55, s31, 0
	s_mov_b32 s17, 1
	v_mov_b32_e32 v16, 0
	s_branch .LBB0_1604

.LBB0_1710:
	s_cmp_gt_i32 s69, 9
	s_cselect_b64 s[0:1], -1, 0
	s_and_b64 s[2:3], s[6:7], s[0:1]
	s_andn2_b64 vcc, exec, s[2:3]
	s_cbranch_vccnz .LBB0_1764
	s_waitcnt vmcnt(0)
	s_waitcnt vmcnt(0) lgkmcnt(0)
	s_barrier
	v_mov_b32_e32 v0, 0x20040
	ds_read_b32 v2, v0
	ds_read_b32 v3, v0 offset:16
	ds_read_b32 v5, v0 offset:8
	s_lshl_b32 s4, s33, 7
	s_add_u32 s4, s4, 0x3600
	v_lshl_add_u32 v0, v199, 2, s4
	v_mov_b32_e32 v6, 5
	s_waitcnt lgkmcnt(0)
	v_cmp_eq_u32_e32 vcc, 0, v3
	s_cbranch_vccnz .Lxl_orig_8
	v_cmp_lt_u32_e32 vcc, 32, v2
	s_cbranch_vccnz .Lxl_orig_8
	v_lshl_add_u32 v1, v5, 2, s4
	v_cmp_lt_u32_e32 vcc, v199, v2
	s_and_saveexec_b64 s[2:3], vcc
	s_cbranch_execz .LBB0_1763
	v_cmp_eq_u32_e32 vcc, 0, v199
	s_and_saveexec_b64 s[4:5], vcc
	global_store_dword v1, v6, s[92:93]
	s_mov_b64 exec, s[4:5]
	buffer_inv sc1
	s_mov_b32 s4, 0x20000
.Lxl_poll_8:
	global_load_dword v4, v0, s[92:93] sc1
	s_waitcnt vmcnt(0)
	v_cmp_gt_u32_e32 vcc, 5, v4
	s_cbranch_vccz .LBB0_1763
	s_sleep 1
	s_sub_u32 s4, s4, 1
	s_cmp_lg_u32 s4, 0
	s_cbranch_scc1 .Lxl_poll_8
	s_branch .LBB0_1763
.Lxl_orig_8:
	s_mov_b64 s[2:3], exec
	v_readlane_b32 s4, v255, 1
	v_readlane_b32 s5, v255, 2
	s_and_b64 s[4:5], s[2:3], s[4:5]
	s_mov_b64 exec, s[4:5]
	s_cbranch_execz .LBB0_1763
	s_add_i32 s4, 0, 0x20040
	v_mov_b32_e32 v0, s4
	s_waitcnt vmcnt(0) expcnt(0) lgkmcnt(0)
	ds_read_b32 v2, v0
	s_add_i32 s4, 0, 0x20044
	v_mov_b32_e32 v0, s4
	ds_read_b32 v0, v0
	s_waitcnt lgkmcnt(1)
	v_cmp_ne_u32_e32 vcc, 0, v2
	s_cbranch_vccnz .LBB0_1727
	v_readlane_b32 s4, v255, 0
	s_mul_i32 s35, s35, s4
	s_add_u32 s4, s30, 0xfc00200
	s_addc_u32 s5, s31, 0
	s_add_u32 s6, s30, 0xfc00400
	s_addc_u32 s7, s31, 0
	s_add_u32 s8, s30, 0xfc00500
	s_addc_u32 s9, s31, 0
	s_add_u32 s10, s30, 0xfc00600
	s_addc_u32 s11, s31, 0
	s_add_u32 s12, s30, 0xfc00700
	s_addc_u32 s13, s31, 0
	s_add_u32 s14, s30, 0xfc00800
	s_addc_u32 s15, s31, 0
	s_add_u32 s16, s30, 0xfc00900
	s_addc_u32 s17, s31, 0
	s_add_u32 s18, s30, 0xfc00a00
	s_addc_u32 s19, s31, 0
	s_add_u32 s20, s30, 0xfc00b00
	s_addc_u32 s21, s31, 0
	s_add_u32 s22, s30, 0xfc00c00
	s_addc_u32 s23, s31, 0
	s_add_u32 s24, s30, 0xfc00d00
	s_addc_u32 s25, s31, 0
	s_add_u32 s26, s30, 0xfc00e00
	s_addc_u32 s27, s31, 0
	s_add_u32 s40, s30, 0xfc00f00
	s_addc_u32 s41, s31, 0
	s_add_u32 s42, s30, 0xfc01000
	s_addc_u32 s43, s31, 0
	s_add_u32 s44, s30, 0xfc01100
	s_addc_u32 s45, s31, 0
	s_add_u32 s46, s30, 0xfc01200
	s_addc_u32 s47, s31, 0
	s_add_u32 s48, s30, 0xfc01300
	s_mul_i32 s35, s35, s34
	s_addc_u32 s49, s31, 0
	s_mov_b32 s39, 1
	v_mov_b32_e32 v16, 0
	s_branch .LBB0_1715
